# v20 plus: straight-line sigmoid+store path for the MO column tiles (latent rows), context-row MO tiles skip the epilogue
# speedup vs baseline: 1.0270x; 1.0000x over previous
; __device__ __forceinline__ float sigmoid_f(float x) { return __builtin_amdgcn_rcpf(1.0f + __expf(-x)); }
;     __device__ __forceinline__ void st4(bf16_t* p, f32x4 v) const { u32x2 w; w.x = cvt_pk_bf16(v[0], v[1]); w.y = cvt_pk_bf16(v[2], v[3]); *(u32x2*)p = w; }
;     __device__ __forceinline__ void operator()(const f32x4 (&acc)[2][2][4][2], const pg8::Unit& u, int wr, int wc, int fr, int fq) const {
;     ...
;                             const int cc = cc0 + bj * 128 + n * 16; const f32x4 v = acc[ai][bj][m][n];
;                             if (pn == 5) st4(V + ((size_t)bidx * SKV + (isctx ? tok : TCX + tok)) * 256 + cc, v);
;                             else if (pn < 14) st4(MQK + (size_t)gr * 2048 + (pn - 6) * 256 + cc, v);
;                             else if (pn < 18) st4(MV + (size_t)gr * 1024 + (pn - 14) * 256 + cc, v);
;                             else if (pn < 22) { if (!isctx) { f32x4 s; s[0] = sigmoid_f(v[0]); s[1] = sigmoid_f(v[1]); s[2] = sigmoid_f(v[2]); s[3] = sigmoid_f(v[3]); st4(MO + (size_t)gr * 1024 + (pn - 18) * 256 + cc, s); } }
.LBB0_248:
	s_cmp_lg_u32 s43, 5
	s_cselect_b64 s[20:21], -1, 0
	s_cmp_gt_u32 s43, 13
	s_cselect_b64 s[22:23], -1, 0
	s_cmp_gt_u32 s43, 17
	s_cselect_b64 s[70:71], -1, 0
	s_cmp_gt_u32 s43, 21
	v_readlane_b32 s3, v255, 15
	s_cselect_b64 s[68:69], -1, 0
	s_lshl_b32 s39, s43, 8
	v_ashrrev_i32_e32 v155, 31, v154
	v_lshl_add_u32 v134, v167, 2, s3
	v_cmp_lt_i32_e64 s[36:37], 1, v167
	s_add_i32 s66, s39, 0xfffffa00
	s_mov_b32 s67, s64
	v_lshlrev_b64 v[156:157], 7, v[154:155]
	v_lshlrev_b64 v[144:145], 11, v[154:155]
	v_lshlrev_b64 v[142:143], 12, v[154:155]
	s_cmp_lt_u32 s43, 6
	s_cbranch_scc1 .Lwin_gen
	s_cmp_gt_u32 s43, 21
	s_cbranch_scc1 .Lwin_gen
	s_cmp_gt_u32 s43, 17
	s_cbranch_scc1 .Lwin_mo
	s_cmp_gt_u32 s43, 13
	s_cbranch_scc1 .Lwin_mv
	v_readlane_b32 s16, v255, 27
	v_readlane_b32 s17, v255, 28
	v_ashrrev_i32_e32 v135, 31, v134
	s_nop 1
	v_lshl_add_u64 v[130:131], s[16:17], 0, v[142:143]
	v_lshl_add_u64 v[130:131], s[66:67], 1, v[130:131]
	v_lshl_add_u64 v[130:131], v[134:135], 1, v[130:131]
	s_mov_b64 s[28:29], 0x10000
	s_mov_b64 s[30:31], 0x50000
	s_branch .Lwin_st

; __device__ __forceinline__ unsigned cvt_pk_bf16(float lo, float hi) { unsigned r; asm volatile("v_cvt_pk_bf16_f32 %0, %1, %2" : "=v"(r) : "v"(lo), "v"(hi)); return r; }
; __device__ __forceinline__ float sigmoid_f(float x) { return __builtin_amdgcn_rcpf(1.0f + __expf(-x)); }
;     __device__ __forceinline__ void st4(bf16_t* p, f32x4 v) const { u32x2 w; w.x = cvt_pk_bf16(v[0], v[1]); w.y = cvt_pk_bf16(v[2], v[3]); *(u32x2*)p = w; }
;     __device__ __forceinline__ void operator()(const f32x4 (&acc)[2][2][4][2], const pg8::Unit& u, int wr, int wc, int fr, int fq) const {
;     ...
;                             else if (pn < 22) { if (!isctx) { f32x4 s; s[0] = sigmoid_f(v[0]); s[1] = sigmoid_f(v[1]); s[2] = sigmoid_f(v[2]); s[3] = sigmoid_f(v[3]); st4(MO + (size_t)gr * 1024 + (pn - 18) * 256 + cc, s); } }
.Lwin_mo:
	s_and_b64 vcc, exec, s[46:47]
	s_cbranch_vccnz .LBB0_234
	v_readlane_b32 s16, v255, 33
	v_readlane_b32 s17, v255, 34
	v_ashrrev_i32_e32 v135, 31, v134
	s_add_i32 s28, s39, 0xffffee00
	s_mov_b32 s29, 0
	v_lshl_add_u64 v[130:131], s[16:17], 0, v[144:145]
	v_lshl_add_u64 v[130:131], s[28:29], 1, v[130:131]
	v_lshl_add_u64 v[130:131], v[134:135], 1, v[130:131]
	s_mov_b64 s[28:29], 0x8000
	s_mov_b64 s[30:31], 0x28000
	v_mov_b32_e32 v158, 0xbfb8aa3b
	v_mov_b32_e32 v159, 0xbfb8aa3b
	v_pk_mul_f32 v[132:133], v[126:127], v[158:159]
	v_pk_mul_f32 v[134:135], v[128:129], v[158:159]
	v_pk_mul_f32 v[136:137], v[122:123], v[158:159]
	v_pk_mul_f32 v[138:139], v[124:125], v[158:159]
	v_pk_mul_f32 v[140:141], v[118:119], v[158:159]
	v_pk_mul_f32 v[142:143], v[120:121], v[158:159]
	v_pk_mul_f32 v[144:145], v[114:115], v[158:159]
	v_pk_mul_f32 v[156:157], v[116:117], v[158:159]
	v_exp_f32_e32 v132, v132
	v_exp_f32_e32 v133, v133
	v_exp_f32_e32 v134, v134
	v_exp_f32_e32 v135, v135
	v_exp_f32_e32 v136, v136
	v_exp_f32_e32 v137, v137
	v_exp_f32_e32 v138, v138
	v_exp_f32_e32 v139, v139
	v_exp_f32_e32 v140, v140
	v_exp_f32_e32 v141, v141
	v_exp_f32_e32 v142, v142
	v_exp_f32_e32 v143, v143
	v_exp_f32_e32 v144, v144
	v_exp_f32_e32 v145, v145
	v_exp_f32_e32 v156, v156
	v_exp_f32_e32 v157, v157
	v_pk_add_f32 v[132:133], v[132:133], 1.0 op_sel_hi:[1,0]
	v_pk_add_f32 v[134:135], v[134:135], 1.0 op_sel_hi:[1,0]
	v_pk_add_f32 v[136:137], v[136:137], 1.0 op_sel_hi:[1,0]
	v_pk_add_f32 v[138:139], v[138:139], 1.0 op_sel_hi:[1,0]
	v_pk_add_f32 v[140:141], v[140:141], 1.0 op_sel_hi:[1,0]
	v_pk_add_f32 v[142:143], v[142:143], 1.0 op_sel_hi:[1,0]
	v_pk_add_f32 v[144:145], v[144:145], 1.0 op_sel_hi:[1,0]
	v_pk_add_f32 v[156:157], v[156:157], 1.0 op_sel_hi:[1,0]
	v_rcp_f32_e32 v132, v132
	v_rcp_f32_e32 v133, v133
	v_rcp_f32_e32 v134, v134
	v_rcp_f32_e32 v135, v135
	v_rcp_f32_e32 v136, v136
	v_rcp_f32_e32 v137, v137
	v_rcp_f32_e32 v138, v138
	v_rcp_f32_e32 v139, v139
	v_rcp_f32_e32 v140, v140
	v_rcp_f32_e32 v141, v141
	v_rcp_f32_e32 v142, v142
	v_rcp_f32_e32 v143, v143
	v_rcp_f32_e32 v144, v144
	v_rcp_f32_e32 v145, v145
	v_rcp_f32_e32 v156, v156
	v_rcp_f32_e32 v157, v157
	v_cvt_pk_bf16_f32 v132, v132, v133
	v_cvt_pk_bf16_f32 v133, v134, v135
	v_cvt_pk_bf16_f32 v136, v136, v137
	v_cvt_pk_bf16_f32 v137, v138, v139
	v_cvt_pk_bf16_f32 v140, v140, v141
	v_cvt_pk_bf16_f32 v141, v142, v143
	v_cvt_pk_bf16_f32 v144, v144, v145
	v_cvt_pk_bf16_f32 v145, v156, v157
	global_store_dwordx2 v[130:131], v[132:133], off
	global_store_dwordx2 v[130:131], v[136:137], off offset:32
	global_store_dwordx2 v[130:131], v[140:141], off offset:256
	global_store_dwordx2 v[130:131], v[144:145], off offset:288
	v_lshl_add_u64 v[130:131], v[130:131], 0, s[28:29]
	v_pk_mul_f32 v[132:133], v[110:111], v[158:159]
	v_pk_mul_f32 v[134:135], v[112:113], v[158:159]
	v_pk_mul_f32 v[136:137], v[106:107], v[158:159]
	v_pk_mul_f32 v[138:139], v[108:109], v[158:159]
	v_pk_mul_f32 v[140:141], v[102:103], v[158:159]
	v_pk_mul_f32 v[142:143], v[104:105], v[158:159]
	v_pk_mul_f32 v[144:145], v[98:99], v[158:159]
	v_pk_mul_f32 v[156:157], v[100:101], v[158:159]
	v_exp_f32_e32 v132, v132
	v_exp_f32_e32 v133, v133
	v_exp_f32_e32 v134, v134
	v_exp_f32_e32 v135, v135
	v_exp_f32_e32 v136, v136
	v_exp_f32_e32 v137, v137
	v_exp_f32_e32 v138, v138
	v_exp_f32_e32 v139, v139
	v_exp_f32_e32 v140, v140
	v_exp_f32_e32 v141, v141
	v_exp_f32_e32 v142, v142
	v_exp_f32_e32 v143, v143
	v_exp_f32_e32 v144, v144
	v_exp_f32_e32 v145, v145
	v_exp_f32_e32 v156, v156
	v_exp_f32_e32 v157, v157
	v_pk_add_f32 v[132:133], v[132:133], 1.0 op_sel_hi:[1,0]
	v_pk_add_f32 v[134:135], v[134:135], 1.0 op_sel_hi:[1,0]
	v_pk_add_f32 v[136:137], v[136:137], 1.0 op_sel_hi:[1,0]
	v_pk_add_f32 v[138:139], v[138:139], 1.0 op_sel_hi:[1,0]
	v_pk_add_f32 v[140:141], v[140:141], 1.0 op_sel_hi:[1,0]
	v_pk_add_f32 v[142:143], v[142:143], 1.0 op_sel_hi:[1,0]
	v_pk_add_f32 v[144:145], v[144:145], 1.0 op_sel_hi:[1,0]
	v_pk_add_f32 v[156:157], v[156:157], 1.0 op_sel_hi:[1,0]
	v_rcp_f32_e32 v132, v132
	v_rcp_f32_e32 v133, v133
	v_rcp_f32_e32 v134, v134
	v_rcp_f32_e32 v135, v135
	v_rcp_f32_e32 v136, v136
	v_rcp_f32_e32 v137, v137
	v_rcp_f32_e32 v138, v138
	v_rcp_f32_e32 v139, v139
	v_rcp_f32_e32 v140, v140
	v_rcp_f32_e32 v141, v141
	v_rcp_f32_e32 v142, v142
	v_rcp_f32_e32 v143, v143
	v_rcp_f32_e32 v144, v144
	v_rcp_f32_e32 v145, v145
	v_rcp_f32_e32 v156, v156
	v_rcp_f32_e32 v157, v157
	v_cvt_pk_bf16_f32 v132, v132, v133
	v_cvt_pk_bf16_f32 v133, v134, v135
	v_cvt_pk_bf16_f32 v136, v136, v137
	v_cvt_pk_bf16_f32 v137, v138, v139
	v_cvt_pk_bf16_f32 v140, v140, v141
	v_cvt_pk_bf16_f32 v141, v142, v143
	v_cvt_pk_bf16_f32 v144, v144, v145
	v_cvt_pk_bf16_f32 v145, v156, v157
	global_store_dwordx2 v[130:131], v[132:133], off
	global_store_dwordx2 v[130:131], v[136:137], off offset:32
	global_store_dwordx2 v[130:131], v[140:141], off offset:256
	global_store_dwordx2 v[130:131], v[144:145], off offset:288
	v_lshl_add_u64 v[130:131], v[130:131], 0, s[28:29]
	v_pk_mul_f32 v[132:133], v[92:93], v[158:159]
	v_pk_mul_f32 v[134:135], v[94:95], v[158:159]
	v_pk_mul_f32 v[136:137], v[88:89], v[158:159]
	v_pk_mul_f32 v[138:139], v[90:91], v[158:159]
	v_pk_mul_f32 v[140:141], v[84:85], v[158:159]
	v_pk_mul_f32 v[142:143], v[86:87], v[158:159]
	v_pk_mul_f32 v[144:145], v[80:81], v[158:159]
	v_pk_mul_f32 v[156:157], v[82:83], v[158:159]
	v_exp_f32_e32 v132, v132
	v_exp_f32_e32 v133, v133
	v_exp_f32_e32 v134, v134
	v_exp_f32_e32 v135, v135
	v_exp_f32_e32 v136, v136
	v_exp_f32_e32 v137, v137
	v_exp_f32_e32 v138, v138
	v_exp_f32_e32 v139, v139
	v_exp_f32_e32 v140, v140
	v_exp_f32_e32 v141, v141
; __device__ __forceinline__ float sigmoid_f(float x) { return __builtin_amdgcn_rcpf(1.0f + __expf(-x)); }
;     __device__ __forceinline__ void st4(bf16_t* p, f32x4 v) const { u32x2 w; w.x = cvt_pk_bf16(v[0], v[1]); w.y = cvt_pk_bf16(v[2], v[3]); *(u32x2*)p = w; }
;     __device__ __forceinline__ void operator()(const f32x4 (&acc)[2][2][4][2], const pg8::Unit& u, int wr, int wc, int fr, int fq) const {
;     ...
;                             else if (pn < 22) { if (!isctx) { f32x4 s; s[0] = sigmoid_f(v[0]); s[1] = sigmoid_f(v[1]); s[2] = sigmoid_f(v[2]); s[3] = sigmoid_f(v[3]); st4(MO + (size_t)gr * 1024 + (pn - 18) * 256 + cc, s); } }
	v_exp_f32_e32 v142, v142
	v_exp_f32_e32 v143, v143
	v_exp_f32_e32 v144, v144
	v_exp_f32_e32 v145, v145
	v_exp_f32_e32 v156, v156
	v_exp_f32_e32 v157, v157
	v_pk_add_f32 v[132:133], v[132:133], 1.0 op_sel_hi:[1,0]
	v_pk_add_f32 v[134:135], v[134:135], 1.0 op_sel_hi:[1,0]
	v_pk_add_f32 v[136:137], v[136:137], 1.0 op_sel_hi:[1,0]
	v_pk_add_f32 v[138:139], v[138:139], 1.0 op_sel_hi:[1,0]
	v_pk_add_f32 v[140:141], v[140:141], 1.0 op_sel_hi:[1,0]
	v_pk_add_f32 v[142:143], v[142:143], 1.0 op_sel_hi:[1,0]
	v_pk_add_f32 v[144:145], v[144:145], 1.0 op_sel_hi:[1,0]
	v_pk_add_f32 v[156:157], v[156:157], 1.0 op_sel_hi:[1,0]
	v_rcp_f32_e32 v132, v132
	v_rcp_f32_e32 v133, v133
	v_rcp_f32_e32 v134, v134
	v_rcp_f32_e32 v135, v135
	v_rcp_f32_e32 v136, v136
	v_rcp_f32_e32 v137, v137
	v_rcp_f32_e32 v138, v138
	v_rcp_f32_e32 v139, v139
	v_rcp_f32_e32 v140, v140
	v_rcp_f32_e32 v141, v141
	v_rcp_f32_e32 v142, v142
	v_rcp_f32_e32 v143, v143
	v_rcp_f32_e32 v144, v144
	v_rcp_f32_e32 v145, v145
	v_rcp_f32_e32 v156, v156
	v_rcp_f32_e32 v157, v157
	v_cvt_pk_bf16_f32 v132, v132, v133
	v_cvt_pk_bf16_f32 v133, v134, v135
	v_cvt_pk_bf16_f32 v136, v136, v137
	v_cvt_pk_bf16_f32 v137, v138, v139
	v_cvt_pk_bf16_f32 v140, v140, v141
	v_cvt_pk_bf16_f32 v141, v142, v143
	v_cvt_pk_bf16_f32 v144, v144, v145
	v_cvt_pk_bf16_f32 v145, v156, v157
	global_store_dwordx2 v[130:131], v[132:133], off
	global_store_dwordx2 v[130:131], v[136:137], off offset:32
	global_store_dwordx2 v[130:131], v[140:141], off offset:256
	global_store_dwordx2 v[130:131], v[144:145], off offset:288
	v_lshl_add_u64 v[130:131], v[130:131], 0, s[28:29]
	v_pk_mul_f32 v[132:133], v[76:77], v[158:159]
	v_pk_mul_f32 v[134:135], v[78:79], v[158:159]
	v_pk_mul_f32 v[136:137], v[72:73], v[158:159]
	v_pk_mul_f32 v[138:139], v[74:75], v[158:159]
	v_pk_mul_f32 v[140:141], v[68:69], v[158:159]
	v_pk_mul_f32 v[142:143], v[70:71], v[158:159]
	v_pk_mul_f32 v[144:145], v[64:65], v[158:159]
	v_pk_mul_f32 v[156:157], v[66:67], v[158:159]
	v_exp_f32_e32 v132, v132
	v_exp_f32_e32 v133, v133
	v_exp_f32_e32 v134, v134
	v_exp_f32_e32 v135, v135
	v_exp_f32_e32 v136, v136
	v_exp_f32_e32 v137, v137
	v_exp_f32_e32 v138, v138
	v_exp_f32_e32 v139, v139
	v_exp_f32_e32 v140, v140
	v_exp_f32_e32 v141, v141
	v_exp_f32_e32 v142, v142
	v_exp_f32_e32 v143, v143
	v_exp_f32_e32 v144, v144
	v_exp_f32_e32 v145, v145
	v_exp_f32_e32 v156, v156
	v_exp_f32_e32 v157, v157
	v_pk_add_f32 v[132:133], v[132:133], 1.0 op_sel_hi:[1,0]
	v_pk_add_f32 v[134:135], v[134:135], 1.0 op_sel_hi:[1,0]
	v_pk_add_f32 v[136:137], v[136:137], 1.0 op_sel_hi:[1,0]
	v_pk_add_f32 v[138:139], v[138:139], 1.0 op_sel_hi:[1,0]
	v_pk_add_f32 v[140:141], v[140:141], 1.0 op_sel_hi:[1,0]
	v_pk_add_f32 v[142:143], v[142:143], 1.0 op_sel_hi:[1,0]
	v_pk_add_f32 v[144:145], v[144:145], 1.0 op_sel_hi:[1,0]
	v_pk_add_f32 v[156:157], v[156:157], 1.0 op_sel_hi:[1,0]
	v_rcp_f32_e32 v132, v132
	v_rcp_f32_e32 v133, v133
	v_rcp_f32_e32 v134, v134
	v_rcp_f32_e32 v135, v135
	v_rcp_f32_e32 v136, v136
	v_rcp_f32_e32 v137, v137
	v_rcp_f32_e32 v138, v138
	v_rcp_f32_e32 v139, v139
	v_rcp_f32_e32 v140, v140
	v_rcp_f32_e32 v141, v141
	v_rcp_f32_e32 v142, v142
	v_rcp_f32_e32 v143, v143
	v_rcp_f32_e32 v144, v144
	v_rcp_f32_e32 v145, v145
	v_rcp_f32_e32 v156, v156
	v_rcp_f32_e32 v157, v157
	v_cvt_pk_bf16_f32 v132, v132, v133
	v_cvt_pk_bf16_f32 v133, v134, v135
	v_cvt_pk_bf16_f32 v136, v136, v137
	v_cvt_pk_bf16_f32 v137, v138, v139
	v_cvt_pk_bf16_f32 v140, v140, v141
	v_cvt_pk_bf16_f32 v141, v142, v143
	v_cvt_pk_bf16_f32 v144, v144, v145
	v_cvt_pk_bf16_f32 v145, v156, v157
	global_store_dwordx2 v[130:131], v[132:133], off
	global_store_dwordx2 v[130:131], v[136:137], off offset:32
	global_store_dwordx2 v[130:131], v[140:141], off offset:256
	global_store_dwordx2 v[130:131], v[144:145], off offset:288
	v_lshl_add_u64 v[130:131], v[130:131], 0, s[30:31]
	v_pk_mul_f32 v[132:133], v[60:61], v[158:159]
	v_pk_mul_f32 v[134:135], v[62:63], v[158:159]
	v_pk_mul_f32 v[136:137], v[56:57], v[158:159]
	v_pk_mul_f32 v[138:139], v[58:59], v[158:159]
	v_pk_mul_f32 v[140:141], v[52:53], v[158:159]
	v_pk_mul_f32 v[142:143], v[54:55], v[158:159]
	v_pk_mul_f32 v[144:145], v[48:49], v[158:159]
	v_pk_mul_f32 v[156:157], v[50:51], v[158:159]
	v_exp_f32_e32 v132, v132
	v_exp_f32_e32 v133, v133
	v_exp_f32_e32 v134, v134
	v_exp_f32_e32 v135, v135
	v_exp_f32_e32 v136, v136
	v_exp_f32_e32 v137, v137
	v_exp_f32_e32 v138, v138
	v_exp_f32_e32 v139, v139
	v_exp_f32_e32 v140, v140
	v_exp_f32_e32 v141, v141
	v_exp_f32_e32 v142, v142
	v_exp_f32_e32 v143, v143
	v_exp_f32_e32 v144, v144
	v_exp_f32_e32 v145, v145
	v_exp_f32_e32 v156, v156
	v_exp_f32_e32 v157, v157
	v_pk_add_f32 v[132:133], v[132:133], 1.0 op_sel_hi:[1,0]
	v_pk_add_f32 v[134:135], v[134:135], 1.0 op_sel_hi:[1,0]
	v_pk_add_f32 v[136:137], v[136:137], 1.0 op_sel_hi:[1,0]
	v_pk_add_f32 v[138:139], v[138:139], 1.0 op_sel_hi:[1,0]
	v_pk_add_f32 v[140:141], v[140:141], 1.0 op_sel_hi:[1,0]
	v_pk_add_f32 v[142:143], v[142:143], 1.0 op_sel_hi:[1,0]
	v_pk_add_f32 v[144:145], v[144:145], 1.0 op_sel_hi:[1,0]
	v_pk_add_f32 v[156:157], v[156:157], 1.0 op_sel_hi:[1,0]
	v_rcp_f32_e32 v132, v132
	v_rcp_f32_e32 v133, v133
	v_rcp_f32_e32 v134, v134
	v_rcp_f32_e32 v135, v135
	v_rcp_f32_e32 v136, v136
	v_rcp_f32_e32 v137, v137
	v_rcp_f32_e32 v138, v138
	v_rcp_f32_e32 v139, v139
	v_rcp_f32_e32 v140, v140
	v_rcp_f32_e32 v141, v141
	v_rcp_f32_e32 v142, v142
	v_rcp_f32_e32 v143, v143
	v_rcp_f32_e32 v144, v144
	v_rcp_f32_e32 v145, v145
	v_rcp_f32_e32 v156, v156
	v_rcp_f32_e32 v157, v157
	v_cvt_pk_bf16_f32 v132, v132, v133
	v_cvt_pk_bf16_f32 v133, v134, v135
	v_cvt_pk_bf16_f32 v136, v136, v137
; __device__ __forceinline__ float sigmoid_f(float x) { return __builtin_amdgcn_rcpf(1.0f + __expf(-x)); }
;     __device__ __forceinline__ void st4(bf16_t* p, f32x4 v) const { u32x2 w; w.x = cvt_pk_bf16(v[0], v[1]); w.y = cvt_pk_bf16(v[2], v[3]); *(u32x2*)p = w; }
;     __device__ __forceinline__ void operator()(const f32x4 (&acc)[2][2][4][2], const pg8::Unit& u, int wr, int wc, int fr, int fq) const {
;     ...
;                             else if (pn < 22) { if (!isctx) { f32x4 s; s[0] = sigmoid_f(v[0]); s[1] = sigmoid_f(v[1]); s[2] = sigmoid_f(v[2]); s[3] = sigmoid_f(v[3]); st4(MO + (size_t)gr * 1024 + (pn - 18) * 256 + cc, s); } }
	v_cvt_pk_bf16_f32 v137, v138, v139
	v_cvt_pk_bf16_f32 v140, v140, v141
	v_cvt_pk_bf16_f32 v141, v142, v143
	v_cvt_pk_bf16_f32 v144, v144, v145
	v_cvt_pk_bf16_f32 v145, v156, v157
	global_store_dwordx2 v[130:131], v[132:133], off
	global_store_dwordx2 v[130:131], v[136:137], off offset:32
	global_store_dwordx2 v[130:131], v[140:141], off offset:256
	global_store_dwordx2 v[130:131], v[144:145], off offset:288
	v_lshl_add_u64 v[130:131], v[130:131], 0, s[28:29]
	v_pk_mul_f32 v[132:133], v[44:45], v[158:159]
	v_pk_mul_f32 v[134:135], v[46:47], v[158:159]
	v_pk_mul_f32 v[136:137], v[40:41], v[158:159]
	v_pk_mul_f32 v[138:139], v[42:43], v[158:159]
	v_pk_mul_f32 v[140:141], v[36:37], v[158:159]
	v_pk_mul_f32 v[142:143], v[38:39], v[158:159]
	v_pk_mul_f32 v[144:145], v[32:33], v[158:159]
	v_pk_mul_f32 v[156:157], v[34:35], v[158:159]
	v_exp_f32_e32 v132, v132
	v_exp_f32_e32 v133, v133
	v_exp_f32_e32 v134, v134
	v_exp_f32_e32 v135, v135
	v_exp_f32_e32 v136, v136
	v_exp_f32_e32 v137, v137
	v_exp_f32_e32 v138, v138
	v_exp_f32_e32 v139, v139
	v_exp_f32_e32 v140, v140
	v_exp_f32_e32 v141, v141
	v_exp_f32_e32 v142, v142
	v_exp_f32_e32 v143, v143
	v_exp_f32_e32 v144, v144
	v_exp_f32_e32 v145, v145
	v_exp_f32_e32 v156, v156
	v_exp_f32_e32 v157, v157
	v_pk_add_f32 v[132:133], v[132:133], 1.0 op_sel_hi:[1,0]
	v_pk_add_f32 v[134:135], v[134:135], 1.0 op_sel_hi:[1,0]
	v_pk_add_f32 v[136:137], v[136:137], 1.0 op_sel_hi:[1,0]
	v_pk_add_f32 v[138:139], v[138:139], 1.0 op_sel_hi:[1,0]
	v_pk_add_f32 v[140:141], v[140:141], 1.0 op_sel_hi:[1,0]
	v_pk_add_f32 v[142:143], v[142:143], 1.0 op_sel_hi:[1,0]
	v_pk_add_f32 v[144:145], v[144:145], 1.0 op_sel_hi:[1,0]
	v_pk_add_f32 v[156:157], v[156:157], 1.0 op_sel_hi:[1,0]
	v_rcp_f32_e32 v132, v132
	v_rcp_f32_e32 v133, v133
	v_rcp_f32_e32 v134, v134
	v_rcp_f32_e32 v135, v135
	v_rcp_f32_e32 v136, v136
	v_rcp_f32_e32 v137, v137
	v_rcp_f32_e32 v138, v138
	v_rcp_f32_e32 v139, v139
	v_rcp_f32_e32 v140, v140
	v_rcp_f32_e32 v141, v141
	v_rcp_f32_e32 v142, v142
	v_rcp_f32_e32 v143, v143
	v_rcp_f32_e32 v144, v144
	v_rcp_f32_e32 v145, v145
	v_rcp_f32_e32 v156, v156
	v_rcp_f32_e32 v157, v157
	v_cvt_pk_bf16_f32 v132, v132, v133
	v_cvt_pk_bf16_f32 v133, v134, v135
	v_cvt_pk_bf16_f32 v136, v136, v137
	v_cvt_pk_bf16_f32 v137, v138, v139
	v_cvt_pk_bf16_f32 v140, v140, v141
	v_cvt_pk_bf16_f32 v141, v142, v143
	v_cvt_pk_bf16_f32 v144, v144, v145
	v_cvt_pk_bf16_f32 v145, v156, v157
	global_store_dwordx2 v[130:131], v[132:133], off
	global_store_dwordx2 v[130:131], v[136:137], off offset:32
	global_store_dwordx2 v[130:131], v[140:141], off offset:256
	global_store_dwordx2 v[130:131], v[144:145], off offset:288
	v_lshl_add_u64 v[130:131], v[130:131], 0, s[28:29]
	v_pk_mul_f32 v[132:133], v[28:29], v[158:159]
	v_pk_mul_f32 v[134:135], v[30:31], v[158:159]
	v_pk_mul_f32 v[136:137], v[24:25], v[158:159]
	v_pk_mul_f32 v[138:139], v[26:27], v[158:159]
	v_pk_mul_f32 v[140:141], v[20:21], v[158:159]
	v_pk_mul_f32 v[142:143], v[22:23], v[158:159]
	v_pk_mul_f32 v[144:145], v[16:17], v[158:159]
	v_pk_mul_f32 v[156:157], v[18:19], v[158:159]
	v_exp_f32_e32 v132, v132
	v_exp_f32_e32 v133, v133
	v_exp_f32_e32 v134, v134
	v_exp_f32_e32 v135, v135
	v_exp_f32_e32 v136, v136
	v_exp_f32_e32 v137, v137
	v_exp_f32_e32 v138, v138
	v_exp_f32_e32 v139, v139
	v_exp_f32_e32 v140, v140
	v_exp_f32_e32 v141, v141
	v_exp_f32_e32 v142, v142
	v_exp_f32_e32 v143, v143
	v_exp_f32_e32 v144, v144
	v_exp_f32_e32 v145, v145
	v_exp_f32_e32 v156, v156
	v_exp_f32_e32 v157, v157
	v_pk_add_f32 v[132:133], v[132:133], 1.0 op_sel_hi:[1,0]
; __device__ __forceinline__ float sigmoid_f(float x) { return __builtin_amdgcn_rcpf(1.0f + __expf(-x)); }
;     __device__ __forceinline__ void st4(bf16_t* p, f32x4 v) const { u32x2 w; w.x = cvt_pk_bf16(v[0], v[1]); w.y = cvt_pk_bf16(v[2], v[3]); *(u32x2*)p = w; }
;     __device__ __forceinline__ void operator()(const f32x4 (&acc)[2][2][4][2], const pg8::Unit& u, int wr, int wc, int fr, int fq) const {
;     ...
;                             else if (pn < 22) { if (!isctx) { f32x4 s; s[0] = sigmoid_f(v[0]); s[1] = sigmoid_f(v[1]); s[2] = sigmoid_f(v[2]); s[3] = sigmoid_f(v[3]); st4(MO + (size_t)gr * 1024 + (pn - 18) * 256 + cc, s); } }
	v_pk_add_f32 v[134:135], v[134:135], 1.0 op_sel_hi:[1,0]
	v_pk_add_f32 v[136:137], v[136:137], 1.0 op_sel_hi:[1,0]
	v_pk_add_f32 v[138:139], v[138:139], 1.0 op_sel_hi:[1,0]
	v_pk_add_f32 v[140:141], v[140:141], 1.0 op_sel_hi:[1,0]
	v_pk_add_f32 v[142:143], v[142:143], 1.0 op_sel_hi:[1,0]
	v_pk_add_f32 v[144:145], v[144:145], 1.0 op_sel_hi:[1,0]
	v_pk_add_f32 v[156:157], v[156:157], 1.0 op_sel_hi:[1,0]
	v_rcp_f32_e32 v132, v132
	v_rcp_f32_e32 v133, v133
	v_rcp_f32_e32 v134, v134
	v_rcp_f32_e32 v135, v135
	v_rcp_f32_e32 v136, v136
	v_rcp_f32_e32 v137, v137
	v_rcp_f32_e32 v138, v138
	v_rcp_f32_e32 v139, v139
	v_rcp_f32_e32 v140, v140
	v_rcp_f32_e32 v141, v141
	v_rcp_f32_e32 v142, v142
	v_rcp_f32_e32 v143, v143
	v_rcp_f32_e32 v144, v144
	v_rcp_f32_e32 v145, v145
	v_rcp_f32_e32 v156, v156
	v_rcp_f32_e32 v157, v157
	v_cvt_pk_bf16_f32 v132, v132, v133
	v_cvt_pk_bf16_f32 v133, v134, v135
	v_cvt_pk_bf16_f32 v136, v136, v137
	v_cvt_pk_bf16_f32 v137, v138, v139
	v_cvt_pk_bf16_f32 v140, v140, v141
	v_cvt_pk_bf16_f32 v141, v142, v143
	v_cvt_pk_bf16_f32 v144, v144, v145
	v_cvt_pk_bf16_f32 v145, v156, v157
	global_store_dwordx2 v[130:131], v[132:133], off
	global_store_dwordx2 v[130:131], v[136:137], off offset:32
	global_store_dwordx2 v[130:131], v[140:141], off offset:256
	global_store_dwordx2 v[130:131], v[144:145], off offset:288
	v_lshl_add_u64 v[130:131], v[130:131], 0, s[28:29]
	v_pk_mul_f32 v[132:133], v[12:13], v[158:159]
	v_pk_mul_f32 v[134:135], v[14:15], v[158:159]
	v_pk_mul_f32 v[136:137], v[8:9], v[158:159]
	v_pk_mul_f32 v[138:139], v[10:11], v[158:159]
	v_pk_mul_f32 v[140:141], v[4:5], v[158:159]
	v_pk_mul_f32 v[142:143], v[6:7], v[158:159]
	v_pk_mul_f32 v[144:145], v[0:1], v[158:159]
	v_pk_mul_f32 v[156:157], v[2:3], v[158:159]
	v_exp_f32_e32 v132, v132
	v_exp_f32_e32 v133, v133
	v_exp_f32_e32 v134, v134
	v_exp_f32_e32 v135, v135
	v_exp_f32_e32 v136, v136
	v_exp_f32_e32 v137, v137
	v_exp_f32_e32 v138, v138
	v_exp_f32_e32 v139, v139
	v_exp_f32_e32 v140, v140
	v_exp_f32_e32 v141, v141
	v_exp_f32_e32 v142, v142
	v_exp_f32_e32 v143, v143
	v_exp_f32_e32 v144, v144
	v_exp_f32_e32 v145, v145
	v_exp_f32_e32 v156, v156
	v_exp_f32_e32 v157, v157
	v_pk_add_f32 v[132:133], v[132:133], 1.0 op_sel_hi:[1,0]
	v_pk_add_f32 v[134:135], v[134:135], 1.0 op_sel_hi:[1,0]
	v_pk_add_f32 v[136:137], v[136:137], 1.0 op_sel_hi:[1,0]
	v_pk_add_f32 v[138:139], v[138:139], 1.0 op_sel_hi:[1,0]
	v_pk_add_f32 v[140:141], v[140:141], 1.0 op_sel_hi:[1,0]
	v_pk_add_f32 v[142:143], v[142:143], 1.0 op_sel_hi:[1,0]
	v_pk_add_f32 v[144:145], v[144:145], 1.0 op_sel_hi:[1,0]
	v_pk_add_f32 v[156:157], v[156:157], 1.0 op_sel_hi:[1,0]
	v_rcp_f32_e32 v132, v132
	v_rcp_f32_e32 v133, v133
	v_rcp_f32_e32 v134, v134
	v_rcp_f32_e32 v135, v135
	v_rcp_f32_e32 v136, v136
	v_rcp_f32_e32 v137, v137
	v_rcp_f32_e32 v138, v138
	v_rcp_f32_e32 v139, v139
	v_rcp_f32_e32 v140, v140
	v_rcp_f32_e32 v141, v141
	v_rcp_f32_e32 v142, v142
	v_rcp_f32_e32 v143, v143
	v_rcp_f32_e32 v144, v144
	v_rcp_f32_e32 v145, v145
	v_rcp_f32_e32 v156, v156
	v_rcp_f32_e32 v157, v157
	v_cvt_pk_bf16_f32 v132, v132, v133
	v_cvt_pk_bf16_f32 v133, v134, v135
	v_cvt_pk_bf16_f32 v136, v136, v137
	v_cvt_pk_bf16_f32 v137, v138, v139
	v_cvt_pk_bf16_f32 v140, v140, v141
	v_cvt_pk_bf16_f32 v141, v142, v143
	v_cvt_pk_bf16_f32 v144, v144, v145
	v_cvt_pk_bf16_f32 v145, v156, v157
	global_store_dwordx2 v[130:131], v[132:133], off
	global_store_dwordx2 v[130:131], v[136:137], off offset:32
	global_store_dwordx2 v[130:131], v[140:141], off offset:256
	global_store_dwordx2 v[130:131], v[144:145], off offset:288
	s_branch .LBB0_234
